# v014 + peeled first K-iteration (srcC=0, no accumulator zeroing) also in FFN-down, GLU, even-in, even-out loops
# baseline (speedup 1.0000x reference)
.LBB0_352:
	s_add_u32 s24, s36, 0x100
	s_addc_u32 s25, s37, 0
	s_mov_b32 s26, -2
	s_cmp_lg_u64 s[12:13], 0
	s_cbranch_scc0 .Lsp_LBB0353_plp353
	s_setprio 1
.Lsp_LBB0353_plp353:
	s_add_u32 s36, s0, 0x100
	s_addc_u32 s37, s1, 0
	s_add_i32 s27, 0, 0x10000
	s_cmpk_eq_i32 s26, 0x52
	s_cselect_b32 s69, s65, s37
	s_cselect_b32 s68, s64, s36
	v_add_u32_e32 v144, s27, v146
	s_cselect_b32 s15, s67, s25
	s_cselect_b32 s14, s66, s24
	s_add_i32 s28, 0, 0x14000
	ds_read_b128 v[140:143], v144
	ds_read_b128 v[150:153], v144 offset:1024
	ds_read_b128 v[154:157], v144 offset:2048
	ds_read_b128 v[168:171], v144 offset:3072
	v_add_u32_e32 v144, s28, v146
	ds_read_b128 v[172:175], v144
	ds_read_b128 v[176:179], v144 offset:1024
	ds_read_b128 v[180:183], v144 offset:2048
	ds_read_b128 v[184:187], v144 offset:3072
	v_lshl_add_u64 v[144:145], s[0:1], 0, v[136:137]
	s_add_i32 m0, s59, 0xc000
	ds_read_b128 v[188:191], v148
	ds_read_b128 v[192:195], v148 offset:1024
	ds_read_b128 v[196:199], v148 offset:2048
	ds_read_b128 v[200:203], v148 offset:3072
	ds_read_b128 v[204:207], v148 offset:4096
	ds_read_b128 v[216:219], v148 offset:5120
	ds_read_b128 v[220:223], v148 offset:6144
	ds_read_b128 v[224:227], v148 offset:7168
	global_load_lds_dwordx4 v[144:145], off
	v_lshl_add_u64 v[144:145], s[0:1], 0, v[138:139]
	s_add_i32 m0, s59, 0xe000
	s_nop 0
	global_load_lds_dwordx4 v[144:145], off
	s_waitcnt vmcnt(8)
	s_waitcnt lgkmcnt(0)
	s_barrier
	s_waitcnt lgkmcnt(0)
	v_mfma_f32_16x16x32_bf16 v[126:129], v[140:143], v[188:191], 0
	v_mfma_f32_16x16x32_bf16 v[126:129], v[150:153], v[192:195], v[126:129]
	v_mfma_f32_16x16x32_bf16 v[122:125], v[154:157], v[188:191], 0
	v_mfma_f32_16x16x32_bf16 v[122:125], v[168:171], v[192:195], v[122:125]
	v_mfma_f32_16x16x32_bf16 v[110:113], v[140:143], v[196:199], 0
	v_mfma_f32_16x16x32_bf16 v[110:113], v[150:153], v[200:203], v[110:113]
	v_mfma_f32_16x16x32_bf16 v[106:109], v[154:157], v[196:199], 0
	v_mfma_f32_16x16x32_bf16 v[106:109], v[168:171], v[200:203], v[106:109]
	v_mfma_f32_16x16x32_bf16 v[94:97], v[140:143], v[204:207], 0
	v_mfma_f32_16x16x32_bf16 v[94:97], v[150:153], v[216:219], v[94:97]
	v_mfma_f32_16x16x32_bf16 v[90:93], v[154:157], v[204:207], 0
	v_mfma_f32_16x16x32_bf16 v[90:93], v[168:171], v[216:219], v[90:93]
	v_mfma_f32_16x16x32_bf16 v[78:81], v[140:143], v[220:223], 0
	v_mfma_f32_16x16x32_bf16 v[78:81], v[150:153], v[224:227], v[78:81]
	v_mfma_f32_16x16x32_bf16 v[74:77], v[154:157], v[220:223], 0
	v_mfma_f32_16x16x32_bf16 v[74:77], v[168:171], v[224:227], v[74:77]
	v_mfma_f32_16x16x32_bf16 v[118:121], v[172:175], v[188:191], 0
	v_mfma_f32_16x16x32_bf16 v[118:121], v[176:179], v[192:195], v[118:121]
	v_mfma_f32_16x16x32_bf16 v[114:117], v[180:183], v[188:191], 0
	v_mfma_f32_16x16x32_bf16 v[114:117], v[184:187], v[192:195], v[114:117]
	v_mfma_f32_16x16x32_bf16 v[102:105], v[172:175], v[196:199], 0
	v_mfma_f32_16x16x32_bf16 v[102:105], v[176:179], v[200:203], v[102:105]
	v_mfma_f32_16x16x32_bf16 v[98:101], v[180:183], v[196:199], 0
	v_mfma_f32_16x16x32_bf16 v[98:101], v[184:187], v[200:203], v[98:101]
	v_mfma_f32_16x16x32_bf16 v[86:89], v[172:175], v[204:207], 0
	v_mfma_f32_16x16x32_bf16 v[86:89], v[176:179], v[216:219], v[86:89]
	v_mfma_f32_16x16x32_bf16 v[82:85], v[180:183], v[204:207], 0
	v_mfma_f32_16x16x32_bf16 v[82:85], v[184:187], v[216:219], v[82:85]
	v_mfma_f32_16x16x32_bf16 v[70:73], v[172:175], v[220:223], 0
	v_mfma_f32_16x16x32_bf16 v[70:73], v[176:179], v[224:227], v[70:73]
	v_mfma_f32_16x16x32_bf16 v[66:69], v[180:183], v[220:223], 0
	v_mfma_f32_16x16x32_bf16 v[66:69], v[184:187], v[224:227], v[66:69]
	s_barrier
	s_add_i32 s0, s27, s58
	v_lshl_add_u64 v[144:145], s[14:15], 0, v[158:159]
	s_mov_b32 m0, s0
	ds_read_b128 v[188:191], v148 offset:16384
	ds_read_b128 v[192:195], v148 offset:17408
	ds_read_b128 v[196:199], v148 offset:18432
	ds_read_b128 v[200:203], v148 offset:19456
	ds_read_b128 v[204:207], v148 offset:20480
	ds_read_b128 v[216:219], v148 offset:21504
	ds_read_b128 v[220:223], v148 offset:22528
	ds_read_b128 v[224:227], v148 offset:23552
	global_load_lds_dwordx4 v[144:145], off
	s_add_i32 m0, s0, 0x2000
	s_add_u32 s0, s14, 0x158000
	v_lshl_add_u64 v[228:229], s[14:15], 0, v[134:135]
	s_addc_u32 s1, s15, 0
	s_add_i32 s27, s28, s58
	global_load_lds_dwordx4 v[228:229], off
	v_lshl_add_u64 v[230:231], s[0:1], 0, v[158:159]
	s_mov_b32 m0, s27
	v_lshl_add_u64 v[232:233], s[68:69], 0, v[132:133]
	global_load_lds_dwordx4 v[230:231], off
	v_lshl_add_u64 v[230:231], s[0:1], 0, v[134:135]
	s_add_i32 m0, s27, 0x2000
	s_nop 0
	global_load_lds_dwordx4 v[230:231], off
	v_lshl_add_u64 v[230:231], s[68:69], 0, v[130:131]
	s_mov_b32 m0, s59
	s_nop 0
	global_load_lds_dwordx4 v[230:231], off
	s_mov_b32 m0, s70
	s_nop 0
	global_load_lds_dwordx4 v[232:233], off
	s_waitcnt vmcnt(8)
	s_waitcnt lgkmcnt(0)
	s_barrier
	s_waitcnt lgkmcnt(0)
	v_mfma_f32_16x16x32_bf16 v[62:65], v[140:143], v[188:191], 0
	v_mfma_f32_16x16x32_bf16 v[62:65], v[150:153], v[192:195], v[62:65]
	v_mfma_f32_16x16x32_bf16 v[58:61], v[154:157], v[188:191], 0
	v_mfma_f32_16x16x32_bf16 v[58:61], v[168:171], v[192:195], v[58:61]
	v_mfma_f32_16x16x32_bf16 v[46:49], v[140:143], v[196:199], 0
	v_mfma_f32_16x16x32_bf16 v[46:49], v[150:153], v[200:203], v[46:49]
	v_mfma_f32_16x16x32_bf16 v[42:45], v[154:157], v[196:199], 0
	v_mfma_f32_16x16x32_bf16 v[42:45], v[168:171], v[200:203], v[42:45]
	v_mfma_f32_16x16x32_bf16 v[30:33], v[140:143], v[204:207], 0
	v_mfma_f32_16x16x32_bf16 v[30:33], v[150:153], v[216:219], v[30:33]
	v_mfma_f32_16x16x32_bf16 v[26:29], v[154:157], v[204:207], 0
	v_mfma_f32_16x16x32_bf16 v[26:29], v[168:171], v[216:219], v[26:29]
	v_mfma_f32_16x16x32_bf16 v[14:17], v[140:143], v[220:223], 0
	v_mfma_f32_16x16x32_bf16 v[14:17], v[150:153], v[224:227], v[14:17]
	v_mfma_f32_16x16x32_bf16 v[10:13], v[154:157], v[220:223], 0
	v_mfma_f32_16x16x32_bf16 v[10:13], v[168:171], v[224:227], v[10:13]
	v_mfma_f32_16x16x32_bf16 v[54:57], v[172:175], v[188:191], 0
	v_mfma_f32_16x16x32_bf16 v[54:57], v[176:179], v[192:195], v[54:57]
	v_mfma_f32_16x16x32_bf16 v[50:53], v[180:183], v[188:191], 0
	v_mfma_f32_16x16x32_bf16 v[50:53], v[184:187], v[192:195], v[50:53]
	v_mfma_f32_16x16x32_bf16 v[38:41], v[172:175], v[196:199], 0
	v_mfma_f32_16x16x32_bf16 v[38:41], v[176:179], v[200:203], v[38:41]
	v_mfma_f32_16x16x32_bf16 v[34:37], v[180:183], v[196:199], 0
	v_mfma_f32_16x16x32_bf16 v[34:37], v[184:187], v[200:203], v[34:37]
	v_mfma_f32_16x16x32_bf16 v[22:25], v[172:175], v[204:207], 0
	v_mfma_f32_16x16x32_bf16 v[22:25], v[176:179], v[216:219], v[22:25]
	v_mfma_f32_16x16x32_bf16 v[18:21], v[180:183], v[204:207], 0
	v_mfma_f32_16x16x32_bf16 v[18:21], v[184:187], v[216:219], v[18:21]
	v_mfma_f32_16x16x32_bf16 v[6:9], v[172:175], v[220:223], 0
	v_mfma_f32_16x16x32_bf16 v[6:9], v[176:179], v[224:227], v[6:9]
	v_mfma_f32_16x16x32_bf16 v[2:5], v[180:183], v[220:223], 0
	v_mfma_f32_16x16x32_bf16 v[2:5], v[184:187], v[224:227], v[2:5]
	s_barrier
	s_add_i32 s27, 0, 0x18000
	v_add_u32_e32 v149, s27, v146
	s_add_i32 s28, 0, 0x1c000
	ds_read_b128 v[140:143], v149
	ds_read_b128 v[150:153], v149 offset:1024
	ds_read_b128 v[154:157], v149 offset:2048
	ds_read_b128 v[168:171], v149 offset:3072
	v_add_u32_e32 v149, s28, v146
	ds_read_b128 v[172:175], v149
	ds_read_b128 v[176:179], v149 offset:1024
	ds_read_b128 v[180:183], v149 offset:2048
	ds_read_b128 v[184:187], v149 offset:3072
	s_add_u32 s0, s68, 0x158000
	s_addc_u32 s1, s69, 0
	s_mov_b32 m0, s71
	v_lshl_add_u64 v[234:235], s[0:1], 0, v[130:131]
	ds_read_b128 v[188:191], v148 offset:32768
	ds_read_b128 v[192:195], v148 offset:33792
	ds_read_b128 v[196:199], v148 offset:34816
	ds_read_b128 v[200:203], v148 offset:35840
	ds_read_b128 v[204:207], v148 offset:36864
	ds_read_b128 v[216:219], v148 offset:37888
	ds_read_b128 v[220:223], v148 offset:38912
	ds_read_b128 v[224:227], v148 offset:39936
	global_load_lds_dwordx4 v[234:235], off
	v_lshl_add_u64 v[234:235], s[0:1], 0, v[132:133]
	s_mov_b32 m0, s72
	s_nop 0
	global_load_lds_dwordx4 v[234:235], off
	s_waitcnt vmcnt(8)
	s_waitcnt lgkmcnt(0)
	s_barrier
	s_waitcnt lgkmcnt(0)
	v_mfma_f32_16x16x32_bf16 v[126:129], v[140:143], v[188:191], v[126:129]
	v_mfma_f32_16x16x32_bf16 v[126:129], v[150:153], v[192:195], v[126:129]
	v_mfma_f32_16x16x32_bf16 v[122:125], v[154:157], v[188:191], v[122:125]
	v_mfma_f32_16x16x32_bf16 v[122:125], v[168:171], v[192:195], v[122:125]
	v_mfma_f32_16x16x32_bf16 v[110:113], v[140:143], v[196:199], v[110:113]
	v_mfma_f32_16x16x32_bf16 v[110:113], v[150:153], v[200:203], v[110:113]
	v_mfma_f32_16x16x32_bf16 v[106:109], v[154:157], v[196:199], v[106:109]
	v_mfma_f32_16x16x32_bf16 v[106:109], v[168:171], v[200:203], v[106:109]
	v_mfma_f32_16x16x32_bf16 v[94:97], v[140:143], v[204:207], v[94:97]
	v_mfma_f32_16x16x32_bf16 v[94:97], v[150:153], v[216:219], v[94:97]
	v_mfma_f32_16x16x32_bf16 v[90:93], v[154:157], v[204:207], v[90:93]
	v_mfma_f32_16x16x32_bf16 v[90:93], v[168:171], v[216:219], v[90:93]
	v_mfma_f32_16x16x32_bf16 v[78:81], v[140:143], v[220:223], v[78:81]
	v_mfma_f32_16x16x32_bf16 v[78:81], v[150:153], v[224:227], v[78:81]
	v_mfma_f32_16x16x32_bf16 v[74:77], v[154:157], v[220:223], v[74:77]
	v_mfma_f32_16x16x32_bf16 v[74:77], v[168:171], v[224:227], v[74:77]
	v_mfma_f32_16x16x32_bf16 v[118:121], v[172:175], v[188:191], v[118:121]
	v_mfma_f32_16x16x32_bf16 v[118:121], v[176:179], v[192:195], v[118:121]
	v_mfma_f32_16x16x32_bf16 v[114:117], v[180:183], v[188:191], v[114:117]
	v_mfma_f32_16x16x32_bf16 v[114:117], v[184:187], v[192:195], v[114:117]
	v_mfma_f32_16x16x32_bf16 v[102:105], v[172:175], v[196:199], v[102:105]
	v_mfma_f32_16x16x32_bf16 v[102:105], v[176:179], v[200:203], v[102:105]
	v_mfma_f32_16x16x32_bf16 v[98:101], v[180:183], v[196:199], v[98:101]
	v_mfma_f32_16x16x32_bf16 v[98:101], v[184:187], v[200:203], v[98:101]
	v_mfma_f32_16x16x32_bf16 v[86:89], v[172:175], v[204:207], v[86:89]
	v_mfma_f32_16x16x32_bf16 v[86:89], v[176:179], v[216:219], v[86:89]
	v_mfma_f32_16x16x32_bf16 v[82:85], v[180:183], v[204:207], v[82:85]
	v_mfma_f32_16x16x32_bf16 v[82:85], v[184:187], v[216:219], v[82:85]
	v_mfma_f32_16x16x32_bf16 v[70:73], v[172:175], v[220:223], v[70:73]
	v_mfma_f32_16x16x32_bf16 v[70:73], v[176:179], v[224:227], v[70:73]
	v_mfma_f32_16x16x32_bf16 v[66:69], v[180:183], v[220:223], v[66:69]
	v_mfma_f32_16x16x32_bf16 v[66:69], v[184:187], v[224:227], v[66:69]
	s_barrier
	s_add_i32 s0, s27, s58
	v_lshl_add_u64 v[144:145], v[144:145], 0, s[56:57]
	s_mov_b32 m0, s0
	ds_read_b128 v[188:191], v148 offset:49152
	ds_read_b128 v[192:195], v148 offset:50176
	ds_read_b128 v[196:199], v148 offset:51200
	ds_read_b128 v[200:203], v148 offset:52224
	ds_read_b128 v[204:207], v148 offset:53248
	ds_read_b128 v[216:219], v148 offset:54272
	ds_read_b128 v[220:223], v148 offset:55296
	ds_read_b128 v[224:227], v148 offset:56320
	global_load_lds_dwordx4 v[144:145], off
	s_add_i32 m0, s0, 0x2000
	s_add_u32 s0, s14, 0x158080
	v_lshl_add_u64 v[144:145], v[228:229], 0, s[56:57]
	s_addc_u32 s1, s15, 0
	s_add_i32 s14, s28, s58
	global_load_lds_dwordx4 v[144:145], off
	v_lshl_add_u64 v[144:145], s[0:1], 0, v[158:159]
	s_mov_b32 m0, s14
	s_nop 0
	global_load_lds_dwordx4 v[144:145], off
	v_lshl_add_u64 v[144:145], s[0:1], 0, v[134:135]
	s_add_i32 m0, s14, 0x2000
	s_nop 0
	global_load_lds_dwordx4 v[144:145], off
	v_lshl_add_u64 v[144:145], v[230:231], 0, s[56:57]
	s_mov_b32 m0, s73
	s_nop 0
	global_load_lds_dwordx4 v[144:145], off
	v_lshl_add_u64 v[144:145], v[232:233], 0, s[56:57]
	s_mov_b32 m0, s74
	s_nop 0
	global_load_lds_dwordx4 v[144:145], off
	s_waitcnt vmcnt(8)
	s_waitcnt lgkmcnt(0)
	s_barrier
	s_waitcnt lgkmcnt(0)
	v_mfma_f32_16x16x32_bf16 v[62:65], v[140:143], v[188:191], v[62:65]
	v_mfma_f32_16x16x32_bf16 v[62:65], v[150:153], v[192:195], v[62:65]
	v_mfma_f32_16x16x32_bf16 v[58:61], v[154:157], v[188:191], v[58:61]
	v_mfma_f32_16x16x32_bf16 v[58:61], v[168:171], v[192:195], v[58:61]
	v_mfma_f32_16x16x32_bf16 v[46:49], v[140:143], v[196:199], v[46:49]
	v_mfma_f32_16x16x32_bf16 v[46:49], v[150:153], v[200:203], v[46:49]
	v_mfma_f32_16x16x32_bf16 v[42:45], v[154:157], v[196:199], v[42:45]
	v_mfma_f32_16x16x32_bf16 v[42:45], v[168:171], v[200:203], v[42:45]
	v_mfma_f32_16x16x32_bf16 v[30:33], v[140:143], v[204:207], v[30:33]
	v_mfma_f32_16x16x32_bf16 v[30:33], v[150:153], v[216:219], v[30:33]
	v_mfma_f32_16x16x32_bf16 v[26:29], v[154:157], v[204:207], v[26:29]
	v_mfma_f32_16x16x32_bf16 v[26:29], v[168:171], v[216:219], v[26:29]
	v_mfma_f32_16x16x32_bf16 v[14:17], v[140:143], v[220:223], v[14:17]
	v_mfma_f32_16x16x32_bf16 v[14:17], v[150:153], v[224:227], v[14:17]
	v_mfma_f32_16x16x32_bf16 v[10:13], v[154:157], v[220:223], v[10:13]
	v_mfma_f32_16x16x32_bf16 v[10:13], v[168:171], v[224:227], v[10:13]
	v_mfma_f32_16x16x32_bf16 v[54:57], v[172:175], v[188:191], v[54:57]
	v_mfma_f32_16x16x32_bf16 v[54:57], v[176:179], v[192:195], v[54:57]
	v_mfma_f32_16x16x32_bf16 v[50:53], v[180:183], v[188:191], v[50:53]
	v_mfma_f32_16x16x32_bf16 v[50:53], v[184:187], v[192:195], v[50:53]
	v_mfma_f32_16x16x32_bf16 v[38:41], v[172:175], v[196:199], v[38:41]
	v_mfma_f32_16x16x32_bf16 v[38:41], v[176:179], v[200:203], v[38:41]
	v_mfma_f32_16x16x32_bf16 v[34:37], v[180:183], v[196:199], v[34:37]
	v_mfma_f32_16x16x32_bf16 v[34:37], v[184:187], v[200:203], v[34:37]
	v_mfma_f32_16x16x32_bf16 v[22:25], v[172:175], v[204:207], v[22:25]
	v_mfma_f32_16x16x32_bf16 v[22:25], v[176:179], v[216:219], v[22:25]
	v_mfma_f32_16x16x32_bf16 v[18:21], v[180:183], v[204:207], v[18:21]
	v_mfma_f32_16x16x32_bf16 v[18:21], v[184:187], v[216:219], v[18:21]
	v_mfma_f32_16x16x32_bf16 v[6:9], v[172:175], v[220:223], v[6:9]
	v_mfma_f32_16x16x32_bf16 v[6:9], v[176:179], v[224:227], v[6:9]
	v_mfma_f32_16x16x32_bf16 v[2:5], v[180:183], v[220:223], v[2:5]
	v_mfma_f32_16x16x32_bf16 v[2:5], v[184:187], v[224:227], v[2:5]
	s_barrier
	s_add_i32 s26, s26, 2
	s_add_u32 s24, s24, 0x100
	s_addc_u32 s25, s25, 0
	s_cmpk_gt_u32 s26, 0x53
	s_mov_b64 s[0:1], s[36:37]

.LBB0_714:
	s_ashr_i32 s43, s42, 31
	s_lshl_b64 s[10:11], s[42:43], 20
	v_readlane_b32 s16, v242, 2
	v_readlane_b32 s17, v242, 3
	s_add_u32 s1, s16, s10
	s_addc_u32 s16, s17, s11
	s_and_b64 s[10:11], s[14:15], exec
	s_cselect_b32 s49, s16, s67
	s_cselect_b32 s48, s1, s66
	s_ashr_i32 s39, s38, 31
	s_lshl_b64 s[10:11], s[38:39], 20
	s_add_u32 s50, s3, s10
	s_addc_u32 s51, s58, s11
	s_and_b64 s[10:11], s[14:15], exec
	s_cselect_b32 s1, s51, s69
	s_cselect_b32 s10, s50, s68
	s_add_u32 s66, s66, 0x80080
	s_addc_u32 s67, s67, 0
	s_add_u32 s11, s68, 0x100
	s_addc_u32 s16, s69, 0
	s_mov_b32 s17, -2
	s_cmp_lg_u64 s[22:23], 0
	s_cbranch_scc0 .Lsp_LBB0715_plp715
	s_setprio 1
.Lsp_LBB0715_plp715:
	s_add_u32 s14, s66, 0xfff80080
	s_addc_u32 s15, s67, -1
	s_add_i32 s24, 0, 0x10000
	s_cmp_eq_u32 s17, 28
	s_cselect_b32 s69, s49, s15
	s_cselect_b32 s68, s48, s14
	v_add_u32_e32 v147, s24, v144
	s_cselect_b32 s15, s1, s16
	s_cselect_b32 s14, s10, s11
	s_add_i32 s26, 0, 0x14000
	ds_read_b128 v[140:143], v147
	ds_read_b128 v[148:151], v147 offset:1024
	ds_read_b128 v[152:155], v147 offset:2048
	ds_read_b128 v[168:171], v147 offset:3072
	v_add_u32_e32 v147, s26, v144
	ds_read_b128 v[172:175], v147
	ds_read_b128 v[176:179], v147 offset:1024
	ds_read_b128 v[180:183], v147 offset:2048
	ds_read_b128 v[184:187], v147 offset:3072
	v_lshl_add_u64 v[156:157], s[66:67], 0, v[136:137]
	s_add_i32 m0, s65, 0xc000
	ds_read_b128 v[188:191], v146
	ds_read_b128 v[192:195], v146 offset:1024
	ds_read_b128 v[196:199], v146 offset:2048
	ds_read_b128 v[200:203], v146 offset:3072
	ds_read_b128 v[204:207], v146 offset:4096
	ds_read_b128 v[216:219], v146 offset:5120
	ds_read_b128 v[220:223], v146 offset:6144
	ds_read_b128 v[224:227], v146 offset:7168
	global_load_lds_dwordx4 v[156:157], off
	v_lshl_add_u64 v[156:157], s[66:67], 0, v[138:139]
	s_add_i32 m0, s65, 0xe000
	s_nop 0
	global_load_lds_dwordx4 v[156:157], off
	s_waitcnt vmcnt(8)
	s_waitcnt lgkmcnt(0)
	s_barrier
	s_waitcnt lgkmcnt(0)
	v_mfma_f32_16x16x32_bf16 v[126:129], v[140:143], v[188:191], 0
	v_mfma_f32_16x16x32_bf16 v[126:129], v[148:151], v[192:195], v[126:129]
	v_mfma_f32_16x16x32_bf16 v[118:121], v[152:155], v[188:191], 0
	v_mfma_f32_16x16x32_bf16 v[118:121], v[168:171], v[192:195], v[118:121]
	v_mfma_f32_16x16x32_bf16 v[106:109], v[140:143], v[196:199], 0
	v_mfma_f32_16x16x32_bf16 v[106:109], v[148:151], v[200:203], v[106:109]
	v_mfma_f32_16x16x32_bf16 v[98:101], v[152:155], v[196:199], 0
	v_mfma_f32_16x16x32_bf16 v[98:101], v[168:171], v[200:203], v[98:101]
	v_mfma_f32_16x16x32_bf16 v[90:93], v[140:143], v[204:207], 0
	v_mfma_f32_16x16x32_bf16 v[90:93], v[148:151], v[216:219], v[90:93]
	v_mfma_f32_16x16x32_bf16 v[82:85], v[152:155], v[204:207], 0
	v_mfma_f32_16x16x32_bf16 v[82:85], v[168:171], v[216:219], v[82:85]
	v_mfma_f32_16x16x32_bf16 v[74:77], v[140:143], v[220:223], 0
	v_mfma_f32_16x16x32_bf16 v[74:77], v[148:151], v[224:227], v[74:77]
	v_mfma_f32_16x16x32_bf16 v[66:69], v[152:155], v[220:223], 0
	v_mfma_f32_16x16x32_bf16 v[66:69], v[168:171], v[224:227], v[66:69]
	v_mfma_f32_16x16x32_bf16 v[122:125], v[172:175], v[188:191], 0
	v_mfma_f32_16x16x32_bf16 v[122:125], v[176:179], v[192:195], v[122:125]
	v_mfma_f32_16x16x32_bf16 v[114:117], v[180:183], v[188:191], 0
	v_mfma_f32_16x16x32_bf16 v[114:117], v[184:187], v[192:195], v[114:117]
	v_mfma_f32_16x16x32_bf16 v[110:113], v[172:175], v[196:199], 0
	v_mfma_f32_16x16x32_bf16 v[110:113], v[176:179], v[200:203], v[110:113]
	v_mfma_f32_16x16x32_bf16 v[102:105], v[180:183], v[196:199], 0
	v_mfma_f32_16x16x32_bf16 v[102:105], v[184:187], v[200:203], v[102:105]
	v_mfma_f32_16x16x32_bf16 v[94:97], v[172:175], v[204:207], 0
	v_mfma_f32_16x16x32_bf16 v[94:97], v[176:179], v[216:219], v[94:97]
	v_mfma_f32_16x16x32_bf16 v[86:89], v[180:183], v[204:207], 0
	v_mfma_f32_16x16x32_bf16 v[86:89], v[184:187], v[216:219], v[86:89]
	v_mfma_f32_16x16x32_bf16 v[78:81], v[172:175], v[220:223], 0
	v_mfma_f32_16x16x32_bf16 v[78:81], v[176:179], v[224:227], v[78:81]
	v_mfma_f32_16x16x32_bf16 v[70:73], v[180:183], v[220:223], 0
	v_mfma_f32_16x16x32_bf16 v[70:73], v[184:187], v[224:227], v[70:73]
	s_barrier
	s_add_i32 s24, s24, s59
	v_lshl_add_u64 v[156:157], s[14:15], 0, v[158:159]
	s_mov_b32 m0, s24
	ds_read_b128 v[188:191], v146 offset:16384
	ds_read_b128 v[192:195], v146 offset:17408
	ds_read_b128 v[196:199], v146 offset:18432
	ds_read_b128 v[200:203], v146 offset:19456
	ds_read_b128 v[204:207], v146 offset:20480
	ds_read_b128 v[216:219], v146 offset:21504
	ds_read_b128 v[220:223], v146 offset:22528
	ds_read_b128 v[224:227], v146 offset:23552
	global_load_lds_dwordx4 v[156:157], off
	s_add_i32 m0, s24, 0x2000
	s_add_u32 s24, s14, 0x80000
	v_lshl_add_u64 v[228:229], s[14:15], 0, v[134:135]
	s_addc_u32 s25, s15, 0
	s_add_i32 s26, s26, s59
	global_load_lds_dwordx4 v[228:229], off
	v_lshl_add_u64 v[230:231], s[24:25], 0, v[158:159]
	s_mov_b32 m0, s26
	v_lshl_add_u64 v[232:233], s[68:69], 0, v[132:133]
	global_load_lds_dwordx4 v[230:231], off
	v_lshl_add_u64 v[230:231], s[24:25], 0, v[134:135]
	s_add_i32 m0, s26, 0x2000
	s_nop 0
	global_load_lds_dwordx4 v[230:231], off
	v_lshl_add_u64 v[230:231], s[68:69], 0, v[130:131]
	s_mov_b32 m0, s65
	s_nop 0
	global_load_lds_dwordx4 v[230:231], off
	s_mov_b32 m0, s70
	s_nop 0
	global_load_lds_dwordx4 v[232:233], off
	s_waitcnt vmcnt(8)
	s_waitcnt lgkmcnt(0)
	s_barrier
	s_waitcnt lgkmcnt(0)
	v_mfma_f32_16x16x32_bf16 v[58:61], v[140:143], v[188:191], 0
	v_mfma_f32_16x16x32_bf16 v[58:61], v[148:151], v[192:195], v[58:61]
	v_mfma_f32_16x16x32_bf16 v[50:53], v[152:155], v[188:191], 0
	v_mfma_f32_16x16x32_bf16 v[50:53], v[168:171], v[192:195], v[50:53]
	v_mfma_f32_16x16x32_bf16 v[42:45], v[140:143], v[196:199], 0
	v_mfma_f32_16x16x32_bf16 v[42:45], v[148:151], v[200:203], v[42:45]
	v_mfma_f32_16x16x32_bf16 v[34:37], v[152:155], v[196:199], 0
	v_mfma_f32_16x16x32_bf16 v[34:37], v[168:171], v[200:203], v[34:37]
	v_mfma_f32_16x16x32_bf16 v[26:29], v[140:143], v[204:207], 0
	v_mfma_f32_16x16x32_bf16 v[26:29], v[148:151], v[216:219], v[26:29]
	v_mfma_f32_16x16x32_bf16 v[18:21], v[152:155], v[204:207], 0
	v_mfma_f32_16x16x32_bf16 v[18:21], v[168:171], v[216:219], v[18:21]
	v_mfma_f32_16x16x32_bf16 v[10:13], v[140:143], v[220:223], 0
	v_mfma_f32_16x16x32_bf16 v[10:13], v[148:151], v[224:227], v[10:13]
	v_mfma_f32_16x16x32_bf16 v[2:5], v[152:155], v[220:223], 0
	v_mfma_f32_16x16x32_bf16 v[2:5], v[168:171], v[224:227], v[2:5]
	v_mfma_f32_16x16x32_bf16 v[62:65], v[172:175], v[188:191], 0
	v_mfma_f32_16x16x32_bf16 v[62:65], v[176:179], v[192:195], v[62:65]
	v_mfma_f32_16x16x32_bf16 v[54:57], v[180:183], v[188:191], 0
	v_mfma_f32_16x16x32_bf16 v[54:57], v[184:187], v[192:195], v[54:57]
	v_mfma_f32_16x16x32_bf16 v[46:49], v[172:175], v[196:199], 0
	v_mfma_f32_16x16x32_bf16 v[46:49], v[176:179], v[200:203], v[46:49]
	v_mfma_f32_16x16x32_bf16 v[38:41], v[180:183], v[196:199], 0
	v_mfma_f32_16x16x32_bf16 v[38:41], v[184:187], v[200:203], v[38:41]
	v_mfma_f32_16x16x32_bf16 v[30:33], v[172:175], v[204:207], 0
	v_mfma_f32_16x16x32_bf16 v[30:33], v[176:179], v[216:219], v[30:33]
	v_mfma_f32_16x16x32_bf16 v[22:25], v[180:183], v[204:207], 0
	v_mfma_f32_16x16x32_bf16 v[22:25], v[184:187], v[216:219], v[22:25]
	v_mfma_f32_16x16x32_bf16 v[14:17], v[172:175], v[220:223], 0
	v_mfma_f32_16x16x32_bf16 v[14:17], v[176:179], v[224:227], v[14:17]
	v_mfma_f32_16x16x32_bf16 v[6:9], v[180:183], v[220:223], 0
	v_mfma_f32_16x16x32_bf16 v[6:9], v[184:187], v[224:227], v[6:9]
	s_barrier
	s_add_i32 s26, 0, 0x18000
	v_add_u32_e32 v147, s26, v144
	s_add_i32 s27, 0, 0x1c000
	ds_read_b128 v[140:143], v147
	ds_read_b128 v[148:151], v147 offset:1024
	ds_read_b128 v[152:155], v147 offset:2048
	ds_read_b128 v[168:171], v147 offset:3072
	v_add_u32_e32 v147, s27, v144
	ds_read_b128 v[172:175], v147
	ds_read_b128 v[176:179], v147 offset:1024
	ds_read_b128 v[180:183], v147 offset:2048
	ds_read_b128 v[184:187], v147 offset:3072
	s_add_u32 s24, s68, 0x80000
	s_addc_u32 s25, s69, 0
	s_mov_b32 m0, s71
	v_lshl_add_u64 v[234:235], s[24:25], 0, v[130:131]
	ds_read_b128 v[188:191], v146 offset:32768
	ds_read_b128 v[192:195], v146 offset:33792
	ds_read_b128 v[196:199], v146 offset:34816
	ds_read_b128 v[200:203], v146 offset:35840
	ds_read_b128 v[204:207], v146 offset:36864
	ds_read_b128 v[216:219], v146 offset:37888
	ds_read_b128 v[220:223], v146 offset:38912
	ds_read_b128 v[224:227], v146 offset:39936
	global_load_lds_dwordx4 v[234:235], off
	v_lshl_add_u64 v[234:235], s[24:25], 0, v[132:133]
	s_mov_b32 m0, s72
	s_nop 0
	global_load_lds_dwordx4 v[234:235], off
	s_waitcnt vmcnt(8)
	s_waitcnt lgkmcnt(0)
	s_barrier
	s_waitcnt lgkmcnt(0)
	v_mfma_f32_16x16x32_bf16 v[126:129], v[140:143], v[188:191], v[126:129]
	v_mfma_f32_16x16x32_bf16 v[126:129], v[148:151], v[192:195], v[126:129]
	v_mfma_f32_16x16x32_bf16 v[118:121], v[152:155], v[188:191], v[118:121]
	v_mfma_f32_16x16x32_bf16 v[118:121], v[168:171], v[192:195], v[118:121]
	v_mfma_f32_16x16x32_bf16 v[106:109], v[140:143], v[196:199], v[106:109]
	v_mfma_f32_16x16x32_bf16 v[106:109], v[148:151], v[200:203], v[106:109]
	v_mfma_f32_16x16x32_bf16 v[98:101], v[152:155], v[196:199], v[98:101]
	v_mfma_f32_16x16x32_bf16 v[98:101], v[168:171], v[200:203], v[98:101]
	v_mfma_f32_16x16x32_bf16 v[90:93], v[140:143], v[204:207], v[90:93]
	v_mfma_f32_16x16x32_bf16 v[90:93], v[148:151], v[216:219], v[90:93]
	v_mfma_f32_16x16x32_bf16 v[82:85], v[152:155], v[204:207], v[82:85]
	v_mfma_f32_16x16x32_bf16 v[82:85], v[168:171], v[216:219], v[82:85]
	v_mfma_f32_16x16x32_bf16 v[74:77], v[140:143], v[220:223], v[74:77]
	v_mfma_f32_16x16x32_bf16 v[74:77], v[148:151], v[224:227], v[74:77]
	v_mfma_f32_16x16x32_bf16 v[66:69], v[152:155], v[220:223], v[66:69]
	v_mfma_f32_16x16x32_bf16 v[66:69], v[168:171], v[224:227], v[66:69]
	v_mfma_f32_16x16x32_bf16 v[122:125], v[172:175], v[188:191], v[122:125]
	v_mfma_f32_16x16x32_bf16 v[122:125], v[176:179], v[192:195], v[122:125]
	v_mfma_f32_16x16x32_bf16 v[114:117], v[180:183], v[188:191], v[114:117]
	v_mfma_f32_16x16x32_bf16 v[114:117], v[184:187], v[192:195], v[114:117]
	v_mfma_f32_16x16x32_bf16 v[110:113], v[172:175], v[196:199], v[110:113]
	v_mfma_f32_16x16x32_bf16 v[110:113], v[176:179], v[200:203], v[110:113]
	v_mfma_f32_16x16x32_bf16 v[102:105], v[180:183], v[196:199], v[102:105]
	v_mfma_f32_16x16x32_bf16 v[102:105], v[184:187], v[200:203], v[102:105]
	v_mfma_f32_16x16x32_bf16 v[94:97], v[172:175], v[204:207], v[94:97]
	v_mfma_f32_16x16x32_bf16 v[94:97], v[176:179], v[216:219], v[94:97]
	v_mfma_f32_16x16x32_bf16 v[86:89], v[180:183], v[204:207], v[86:89]
	v_mfma_f32_16x16x32_bf16 v[86:89], v[184:187], v[216:219], v[86:89]
	v_mfma_f32_16x16x32_bf16 v[78:81], v[172:175], v[220:223], v[78:81]
	v_mfma_f32_16x16x32_bf16 v[78:81], v[176:179], v[224:227], v[78:81]
	v_mfma_f32_16x16x32_bf16 v[70:73], v[180:183], v[220:223], v[70:73]
	v_mfma_f32_16x16x32_bf16 v[70:73], v[184:187], v[224:227], v[70:73]
	s_barrier
	s_add_i32 s24, s26, s59
	v_lshl_add_u64 v[156:157], v[156:157], 0, s[56:57]
	s_mov_b32 m0, s24
	ds_read_b128 v[188:191], v146 offset:49152
	ds_read_b128 v[192:195], v146 offset:50176
	ds_read_b128 v[196:199], v146 offset:51200
	ds_read_b128 v[200:203], v146 offset:52224
	ds_read_b128 v[204:207], v146 offset:53248
	ds_read_b128 v[216:219], v146 offset:54272
	ds_read_b128 v[220:223], v146 offset:55296
	ds_read_b128 v[224:227], v146 offset:56320
	global_load_lds_dwordx4 v[156:157], off
	s_add_i32 m0, s24, 0x2000
	s_add_u32 s14, s14, 0x80080
	v_lshl_add_u64 v[156:157], v[228:229], 0, s[56:57]
	s_addc_u32 s15, s15, 0
	s_add_i32 s24, s27, s59
	global_load_lds_dwordx4 v[156:157], off
	v_lshl_add_u64 v[156:157], s[14:15], 0, v[158:159]
	s_mov_b32 m0, s24
	s_nop 0
	global_load_lds_dwordx4 v[156:157], off
	v_lshl_add_u64 v[156:157], s[14:15], 0, v[134:135]
	s_add_i32 m0, s24, 0x2000
	s_nop 0
	global_load_lds_dwordx4 v[156:157], off
	v_lshl_add_u64 v[156:157], v[230:231], 0, s[56:57]
	s_mov_b32 m0, s54
	s_nop 0
	global_load_lds_dwordx4 v[156:157], off
	v_lshl_add_u64 v[156:157], v[232:233], 0, s[56:57]
	s_mov_b32 m0, s73
	s_nop 0
	global_load_lds_dwordx4 v[156:157], off
	s_waitcnt vmcnt(8)
	s_waitcnt lgkmcnt(0)
	s_barrier
	s_waitcnt lgkmcnt(0)
	v_mfma_f32_16x16x32_bf16 v[58:61], v[140:143], v[188:191], v[58:61]
	v_mfma_f32_16x16x32_bf16 v[58:61], v[148:151], v[192:195], v[58:61]
	v_mfma_f32_16x16x32_bf16 v[50:53], v[152:155], v[188:191], v[50:53]
	v_mfma_f32_16x16x32_bf16 v[50:53], v[168:171], v[192:195], v[50:53]
	v_mfma_f32_16x16x32_bf16 v[42:45], v[140:143], v[196:199], v[42:45]
	v_mfma_f32_16x16x32_bf16 v[42:45], v[148:151], v[200:203], v[42:45]
	v_mfma_f32_16x16x32_bf16 v[34:37], v[152:155], v[196:199], v[34:37]
	v_mfma_f32_16x16x32_bf16 v[34:37], v[168:171], v[200:203], v[34:37]
	v_mfma_f32_16x16x32_bf16 v[26:29], v[140:143], v[204:207], v[26:29]
	v_mfma_f32_16x16x32_bf16 v[26:29], v[148:151], v[216:219], v[26:29]
	v_mfma_f32_16x16x32_bf16 v[18:21], v[152:155], v[204:207], v[18:21]
	v_mfma_f32_16x16x32_bf16 v[18:21], v[168:171], v[216:219], v[18:21]
	v_mfma_f32_16x16x32_bf16 v[10:13], v[140:143], v[220:223], v[10:13]
	v_mfma_f32_16x16x32_bf16 v[10:13], v[148:151], v[224:227], v[10:13]
	v_mfma_f32_16x16x32_bf16 v[2:5], v[152:155], v[220:223], v[2:5]
	v_mfma_f32_16x16x32_bf16 v[2:5], v[168:171], v[224:227], v[2:5]
	v_mfma_f32_16x16x32_bf16 v[62:65], v[172:175], v[188:191], v[62:65]
	v_mfma_f32_16x16x32_bf16 v[62:65], v[176:179], v[192:195], v[62:65]
	v_mfma_f32_16x16x32_bf16 v[54:57], v[180:183], v[188:191], v[54:57]
	v_mfma_f32_16x16x32_bf16 v[54:57], v[184:187], v[192:195], v[54:57]
	v_mfma_f32_16x16x32_bf16 v[46:49], v[172:175], v[196:199], v[46:49]
	v_mfma_f32_16x16x32_bf16 v[46:49], v[176:179], v[200:203], v[46:49]
	v_mfma_f32_16x16x32_bf16 v[38:41], v[180:183], v[196:199], v[38:41]
	v_mfma_f32_16x16x32_bf16 v[38:41], v[184:187], v[200:203], v[38:41]
	v_mfma_f32_16x16x32_bf16 v[30:33], v[172:175], v[204:207], v[30:33]
	v_mfma_f32_16x16x32_bf16 v[30:33], v[176:179], v[216:219], v[30:33]
	v_mfma_f32_16x16x32_bf16 v[22:25], v[180:183], v[204:207], v[22:25]
	v_mfma_f32_16x16x32_bf16 v[22:25], v[184:187], v[216:219], v[22:25]
	v_mfma_f32_16x16x32_bf16 v[14:17], v[172:175], v[220:223], v[14:17]
	v_mfma_f32_16x16x32_bf16 v[14:17], v[176:179], v[224:227], v[14:17]
	v_mfma_f32_16x16x32_bf16 v[6:9], v[180:183], v[220:223], v[6:9]
	v_mfma_f32_16x16x32_bf16 v[6:9], v[184:187], v[224:227], v[6:9]
	s_barrier
	s_add_i32 s17, s17, 2
	s_add_u32 s66, s66, 0x100
	s_addc_u32 s67, s67, 0
	s_add_u32 s11, s11, 0x100
	s_addc_u32 s16, s16, 0
	s_cmp_gt_u32 s17, 29

.LBB0_800:
	s_ashr_i32 s41, s40, 31
	s_lshl_b64 s[16:17], s[40:41], 20
	s_add_u32 s1, s94, s16
	s_addc_u32 s23, s95, s17
	s_and_b64 s[16:17], s[14:15], exec
	s_cselect_b32 s43, s23, s51
	s_cselect_b32 s42, s1, s50
	s_ashr_i32 s23, s22, 31
	s_lshl_b64 s[16:17], s[22:23], 20
	s_add_u32 s48, s3, s16
	s_addc_u32 s49, s10, s17
	s_and_b64 s[14:15], s[14:15], exec
	s_cselect_b32 s1, s49, s65
	s_cselect_b32 s16, s48, s64
	s_add_u32 s50, s50, 0x80080
	s_addc_u32 s51, s51, 0
	s_add_u32 s17, s64, 0x100
	s_addc_u32 s23, s65, 0
	s_mov_b32 s29, -2
	s_cmp_lg_u64 s[20:21], 0
	s_cbranch_scc0 .Lsp_LBB0801_plp801
	s_setprio 1
.Lsp_LBB0801_plp801:
	s_add_u32 s14, s50, 0xfff80080
	s_addc_u32 s15, s51, -1
	s_add_i32 s30, 0, 0x10000
	s_cmp_eq_u32 s29, 28
	s_cselect_b32 s65, s43, s15
	s_cselect_b32 s64, s42, s14
	v_add_u32_e32 v150, s30, v152
	s_cselect_b32 s15, s1, s23
	s_cselect_b32 s14, s16, s17
	s_add_i32 s34, 0, 0x14000
	ds_read_b128 v[142:145], v150
	ds_read_b128 v[146:149], v150 offset:1024
	ds_read_b128 v[168:171], v150 offset:2048
	ds_read_b128 v[172:175], v150 offset:3072
	v_add_u32_e32 v150, s34, v152
	ds_read_b128 v[176:179], v150
	ds_read_b128 v[180:183], v150 offset:1024
	ds_read_b128 v[184:187], v150 offset:2048
	ds_read_b128 v[188:191], v150 offset:3072
	v_lshl_add_u64 v[150:151], s[50:51], 0, v[138:139]
	s_add_i32 m0, s58, 0xc000
	ds_read_b128 v[192:195], v155
	ds_read_b128 v[196:199], v155 offset:1024
	ds_read_b128 v[200:203], v155 offset:2048
	ds_read_b128 v[204:207], v155 offset:3072
	ds_read_b128 v[216:219], v155 offset:4096
	ds_read_b128 v[220:223], v155 offset:5120
	ds_read_b128 v[224:227], v155 offset:6144
	ds_read_b128 v[228:231], v155 offset:7168
	global_load_lds_dwordx4 v[150:151], off
	v_lshl_add_u64 v[150:151], s[50:51], 0, v[140:141]
	s_add_i32 m0, s58, 0xe000
	s_nop 0
	global_load_lds_dwordx4 v[150:151], off
	s_waitcnt vmcnt(8)
	s_waitcnt lgkmcnt(0)
	s_barrier
	s_waitcnt lgkmcnt(0)
	v_mfma_f32_16x16x32_bf16 v[126:129], v[142:145], v[192:195], 0
	v_mfma_f32_16x16x32_bf16 v[126:129], v[146:149], v[196:199], v[126:129]
	v_mfma_f32_16x16x32_bf16 v[122:125], v[168:171], v[192:195], 0
	v_mfma_f32_16x16x32_bf16 v[122:125], v[172:175], v[196:199], v[122:125]
	v_mfma_f32_16x16x32_bf16 v[110:113], v[142:145], v[200:203], 0
	v_mfma_f32_16x16x32_bf16 v[110:113], v[146:149], v[204:207], v[110:113]
	v_mfma_f32_16x16x32_bf16 v[106:109], v[168:171], v[200:203], 0
	v_mfma_f32_16x16x32_bf16 v[106:109], v[172:175], v[204:207], v[106:109]
	v_mfma_f32_16x16x32_bf16 v[94:97], v[142:145], v[216:219], 0
	v_mfma_f32_16x16x32_bf16 v[94:97], v[146:149], v[220:223], v[94:97]
	v_mfma_f32_16x16x32_bf16 v[90:93], v[168:171], v[216:219], 0
	v_mfma_f32_16x16x32_bf16 v[90:93], v[172:175], v[220:223], v[90:93]
	v_mfma_f32_16x16x32_bf16 v[78:81], v[142:145], v[224:227], 0
	v_mfma_f32_16x16x32_bf16 v[78:81], v[146:149], v[228:231], v[78:81]
	v_mfma_f32_16x16x32_bf16 v[74:77], v[168:171], v[224:227], 0
	v_mfma_f32_16x16x32_bf16 v[74:77], v[172:175], v[228:231], v[74:77]
	v_mfma_f32_16x16x32_bf16 v[118:121], v[176:179], v[192:195], 0
	v_mfma_f32_16x16x32_bf16 v[118:121], v[180:183], v[196:199], v[118:121]
	v_mfma_f32_16x16x32_bf16 v[114:117], v[184:187], v[192:195], 0
	v_mfma_f32_16x16x32_bf16 v[114:117], v[188:191], v[196:199], v[114:117]
	v_mfma_f32_16x16x32_bf16 v[102:105], v[176:179], v[200:203], 0
	v_mfma_f32_16x16x32_bf16 v[102:105], v[180:183], v[204:207], v[102:105]
	v_mfma_f32_16x16x32_bf16 v[98:101], v[184:187], v[200:203], 0
	v_mfma_f32_16x16x32_bf16 v[98:101], v[188:191], v[204:207], v[98:101]
	v_mfma_f32_16x16x32_bf16 v[86:89], v[176:179], v[216:219], 0
	v_mfma_f32_16x16x32_bf16 v[86:89], v[180:183], v[220:223], v[86:89]
	v_mfma_f32_16x16x32_bf16 v[82:85], v[184:187], v[216:219], 0
	v_mfma_f32_16x16x32_bf16 v[82:85], v[188:191], v[220:223], v[82:85]
	v_mfma_f32_16x16x32_bf16 v[70:73], v[176:179], v[224:227], 0
	v_mfma_f32_16x16x32_bf16 v[70:73], v[180:183], v[228:231], v[70:73]
	v_mfma_f32_16x16x32_bf16 v[66:69], v[184:187], v[224:227], 0
	v_mfma_f32_16x16x32_bf16 v[66:69], v[188:191], v[228:231], v[66:69]
	s_barrier
	s_add_i32 s30, s30, s11
	v_lshl_add_u64 v[150:151], s[14:15], 0, v[158:159]
	s_mov_b32 m0, s30
	ds_read_b128 v[192:195], v155 offset:16384
	ds_read_b128 v[196:199], v155 offset:17408
	ds_read_b128 v[200:203], v155 offset:18432
	ds_read_b128 v[204:207], v155 offset:19456
	ds_read_b128 v[216:219], v155 offset:20480
	ds_read_b128 v[220:223], v155 offset:21504
	ds_read_b128 v[224:227], v155 offset:22528
	ds_read_b128 v[228:231], v155 offset:23552
	global_load_lds_dwordx4 v[150:151], off
	s_add_i32 m0, s30, 0x2000
	s_add_u32 s30, s14, 0x80000
	v_lshl_add_u64 v[156:157], s[14:15], 0, v[134:135]
	s_addc_u32 s31, s15, 0
	s_add_i32 s34, s34, s11
	global_load_lds_dwordx4 v[156:157], off
	v_lshl_add_u64 v[232:233], s[30:31], 0, v[158:159]
	s_mov_b32 m0, s34
	v_lshl_add_u64 v[234:235], s[64:65], 0, v[132:133]
	global_load_lds_dwordx4 v[232:233], off
	v_lshl_add_u64 v[232:233], s[30:31], 0, v[134:135]
	s_add_i32 m0, s34, 0x2000
	s_nop 0
	global_load_lds_dwordx4 v[232:233], off
	v_lshl_add_u64 v[232:233], s[64:65], 0, v[130:131]
	s_mov_b32 m0, s58
	s_nop 0
	global_load_lds_dwordx4 v[232:233], off
	s_mov_b32 m0, s24
	s_nop 0
	global_load_lds_dwordx4 v[234:235], off
	s_waitcnt vmcnt(8)
	s_waitcnt lgkmcnt(0)
	s_barrier
	s_waitcnt lgkmcnt(0)
	v_mfma_f32_16x16x32_bf16 v[62:65], v[142:145], v[192:195], 0
	v_mfma_f32_16x16x32_bf16 v[62:65], v[146:149], v[196:199], v[62:65]
	v_mfma_f32_16x16x32_bf16 v[58:61], v[168:171], v[192:195], 0
	v_mfma_f32_16x16x32_bf16 v[58:61], v[172:175], v[196:199], v[58:61]
	v_mfma_f32_16x16x32_bf16 v[46:49], v[142:145], v[200:203], 0
	v_mfma_f32_16x16x32_bf16 v[46:49], v[146:149], v[204:207], v[46:49]
	v_mfma_f32_16x16x32_bf16 v[42:45], v[168:171], v[200:203], 0
	v_mfma_f32_16x16x32_bf16 v[42:45], v[172:175], v[204:207], v[42:45]
	v_mfma_f32_16x16x32_bf16 v[30:33], v[142:145], v[216:219], 0
	v_mfma_f32_16x16x32_bf16 v[30:33], v[146:149], v[220:223], v[30:33]
	v_mfma_f32_16x16x32_bf16 v[26:29], v[168:171], v[216:219], 0
	v_mfma_f32_16x16x32_bf16 v[26:29], v[172:175], v[220:223], v[26:29]
	v_mfma_f32_16x16x32_bf16 v[14:17], v[142:145], v[224:227], 0
	v_mfma_f32_16x16x32_bf16 v[14:17], v[146:149], v[228:231], v[14:17]
	v_mfma_f32_16x16x32_bf16 v[10:13], v[168:171], v[224:227], 0
	v_mfma_f32_16x16x32_bf16 v[10:13], v[172:175], v[228:231], v[10:13]
	v_mfma_f32_16x16x32_bf16 v[54:57], v[176:179], v[192:195], 0
	v_mfma_f32_16x16x32_bf16 v[54:57], v[180:183], v[196:199], v[54:57]
	v_mfma_f32_16x16x32_bf16 v[50:53], v[184:187], v[192:195], 0
	v_mfma_f32_16x16x32_bf16 v[50:53], v[188:191], v[196:199], v[50:53]
	v_mfma_f32_16x16x32_bf16 v[38:41], v[176:179], v[200:203], 0
	v_mfma_f32_16x16x32_bf16 v[38:41], v[180:183], v[204:207], v[38:41]
	v_mfma_f32_16x16x32_bf16 v[34:37], v[184:187], v[200:203], 0
	v_mfma_f32_16x16x32_bf16 v[34:37], v[188:191], v[204:207], v[34:37]
	v_mfma_f32_16x16x32_bf16 v[22:25], v[176:179], v[216:219], 0
	v_mfma_f32_16x16x32_bf16 v[22:25], v[180:183], v[220:223], v[22:25]
	v_mfma_f32_16x16x32_bf16 v[18:21], v[184:187], v[216:219], 0
	v_mfma_f32_16x16x32_bf16 v[18:21], v[188:191], v[220:223], v[18:21]
	v_mfma_f32_16x16x32_bf16 v[6:9], v[176:179], v[224:227], 0
	v_mfma_f32_16x16x32_bf16 v[6:9], v[180:183], v[228:231], v[6:9]
	v_mfma_f32_16x16x32_bf16 v[2:5], v[184:187], v[224:227], 0
	v_mfma_f32_16x16x32_bf16 v[2:5], v[188:191], v[228:231], v[2:5]
	s_barrier
	s_add_i32 s34, 0, 0x18000
	v_add_u32_e32 v161, s34, v152
	s_add_i32 s35, 0, 0x1c000
	ds_read_b128 v[142:145], v161
	ds_read_b128 v[146:149], v161 offset:1024
	ds_read_b128 v[168:171], v161 offset:2048
	ds_read_b128 v[172:175], v161 offset:3072
	v_add_u32_e32 v161, s35, v152
	ds_read_b128 v[176:179], v161
	ds_read_b128 v[180:183], v161 offset:1024
	ds_read_b128 v[184:187], v161 offset:2048
	ds_read_b128 v[188:191], v161 offset:3072
	s_add_u32 s30, s64, 0x80000
	s_addc_u32 s31, s65, 0
	s_mov_b32 m0, s25
	v_lshl_add_u64 v[236:237], s[30:31], 0, v[130:131]
	ds_read_b128 v[192:195], v155 offset:32768
	ds_read_b128 v[196:199], v155 offset:33792
	ds_read_b128 v[200:203], v155 offset:34816
	ds_read_b128 v[204:207], v155 offset:35840
	ds_read_b128 v[216:219], v155 offset:36864
	ds_read_b128 v[220:223], v155 offset:37888
	ds_read_b128 v[224:227], v155 offset:38912
	ds_read_b128 v[228:231], v155 offset:39936
	global_load_lds_dwordx4 v[236:237], off
	v_lshl_add_u64 v[236:237], s[30:31], 0, v[132:133]
	s_mov_b32 m0, s59
	s_nop 0
	global_load_lds_dwordx4 v[236:237], off
	s_waitcnt vmcnt(8)
	s_waitcnt lgkmcnt(0)
	s_barrier
	s_waitcnt lgkmcnt(0)
	v_mfma_f32_16x16x32_bf16 v[126:129], v[142:145], v[192:195], v[126:129]
	v_mfma_f32_16x16x32_bf16 v[126:129], v[146:149], v[196:199], v[126:129]
	v_mfma_f32_16x16x32_bf16 v[122:125], v[168:171], v[192:195], v[122:125]
	v_mfma_f32_16x16x32_bf16 v[122:125], v[172:175], v[196:199], v[122:125]
	v_mfma_f32_16x16x32_bf16 v[110:113], v[142:145], v[200:203], v[110:113]
	v_mfma_f32_16x16x32_bf16 v[110:113], v[146:149], v[204:207], v[110:113]
	v_mfma_f32_16x16x32_bf16 v[106:109], v[168:171], v[200:203], v[106:109]
	v_mfma_f32_16x16x32_bf16 v[106:109], v[172:175], v[204:207], v[106:109]
	v_mfma_f32_16x16x32_bf16 v[94:97], v[142:145], v[216:219], v[94:97]
	v_mfma_f32_16x16x32_bf16 v[94:97], v[146:149], v[220:223], v[94:97]
	v_mfma_f32_16x16x32_bf16 v[90:93], v[168:171], v[216:219], v[90:93]
	v_mfma_f32_16x16x32_bf16 v[90:93], v[172:175], v[220:223], v[90:93]
	v_mfma_f32_16x16x32_bf16 v[78:81], v[142:145], v[224:227], v[78:81]
	v_mfma_f32_16x16x32_bf16 v[78:81], v[146:149], v[228:231], v[78:81]
	v_mfma_f32_16x16x32_bf16 v[74:77], v[168:171], v[224:227], v[74:77]
	v_mfma_f32_16x16x32_bf16 v[74:77], v[172:175], v[228:231], v[74:77]
	v_mfma_f32_16x16x32_bf16 v[118:121], v[176:179], v[192:195], v[118:121]
	v_mfma_f32_16x16x32_bf16 v[118:121], v[180:183], v[196:199], v[118:121]
	v_mfma_f32_16x16x32_bf16 v[114:117], v[184:187], v[192:195], v[114:117]
	v_mfma_f32_16x16x32_bf16 v[114:117], v[188:191], v[196:199], v[114:117]
	v_mfma_f32_16x16x32_bf16 v[102:105], v[176:179], v[200:203], v[102:105]
	v_mfma_f32_16x16x32_bf16 v[102:105], v[180:183], v[204:207], v[102:105]
	v_mfma_f32_16x16x32_bf16 v[98:101], v[184:187], v[200:203], v[98:101]
	v_mfma_f32_16x16x32_bf16 v[98:101], v[188:191], v[204:207], v[98:101]
	v_mfma_f32_16x16x32_bf16 v[86:89], v[176:179], v[216:219], v[86:89]
	v_mfma_f32_16x16x32_bf16 v[86:89], v[180:183], v[220:223], v[86:89]
	v_mfma_f32_16x16x32_bf16 v[82:85], v[184:187], v[216:219], v[82:85]
	v_mfma_f32_16x16x32_bf16 v[82:85], v[188:191], v[220:223], v[82:85]
	v_mfma_f32_16x16x32_bf16 v[70:73], v[176:179], v[224:227], v[70:73]
	v_mfma_f32_16x16x32_bf16 v[70:73], v[180:183], v[228:231], v[70:73]
	v_mfma_f32_16x16x32_bf16 v[66:69], v[184:187], v[224:227], v[66:69]
	v_mfma_f32_16x16x32_bf16 v[66:69], v[188:191], v[228:231], v[66:69]
	s_barrier
	s_add_i32 s30, s34, s11
	v_lshl_add_u64 v[150:151], v[150:151], 0, s[56:57]
	s_mov_b32 m0, s30
	ds_read_b128 v[192:195], v155 offset:49152
	ds_read_b128 v[196:199], v155 offset:50176
	ds_read_b128 v[200:203], v155 offset:51200
	ds_read_b128 v[204:207], v155 offset:52224
	ds_read_b128 v[216:219], v155 offset:53248
	ds_read_b128 v[220:223], v155 offset:54272
	ds_read_b128 v[224:227], v155 offset:55296
	ds_read_b128 v[228:231], v155 offset:56320
	global_load_lds_dwordx4 v[150:151], off
	s_add_i32 m0, s30, 0x2000
	s_add_u32 s14, s14, 0x80080
	v_lshl_add_u64 v[150:151], v[156:157], 0, s[56:57]
	s_addc_u32 s15, s15, 0
	s_add_i32 s30, s35, s11
	global_load_lds_dwordx4 v[150:151], off
	v_lshl_add_u64 v[150:151], s[14:15], 0, v[158:159]
	s_mov_b32 m0, s30
	s_nop 0
	global_load_lds_dwordx4 v[150:151], off
	v_lshl_add_u64 v[150:151], s[14:15], 0, v[134:135]
	s_add_i32 m0, s30, 0x2000
	s_nop 0
	global_load_lds_dwordx4 v[150:151], off
	v_lshl_add_u64 v[150:151], v[232:233], 0, s[56:57]
	s_mov_b32 m0, s26
	s_nop 0
	global_load_lds_dwordx4 v[150:151], off
	v_lshl_add_u64 v[150:151], v[234:235], 0, s[56:57]
	s_mov_b32 m0, s27
	s_nop 0
	global_load_lds_dwordx4 v[150:151], off
	s_waitcnt vmcnt(8)
	s_waitcnt lgkmcnt(0)
	s_barrier
	s_waitcnt lgkmcnt(0)
	v_mfma_f32_16x16x32_bf16 v[62:65], v[142:145], v[192:195], v[62:65]
	v_mfma_f32_16x16x32_bf16 v[62:65], v[146:149], v[196:199], v[62:65]
	v_mfma_f32_16x16x32_bf16 v[58:61], v[168:171], v[192:195], v[58:61]
	v_mfma_f32_16x16x32_bf16 v[58:61], v[172:175], v[196:199], v[58:61]
	v_mfma_f32_16x16x32_bf16 v[46:49], v[142:145], v[200:203], v[46:49]
	v_mfma_f32_16x16x32_bf16 v[46:49], v[146:149], v[204:207], v[46:49]
	v_mfma_f32_16x16x32_bf16 v[42:45], v[168:171], v[200:203], v[42:45]
	v_mfma_f32_16x16x32_bf16 v[42:45], v[172:175], v[204:207], v[42:45]
	v_mfma_f32_16x16x32_bf16 v[30:33], v[142:145], v[216:219], v[30:33]
	v_mfma_f32_16x16x32_bf16 v[30:33], v[146:149], v[220:223], v[30:33]
	v_mfma_f32_16x16x32_bf16 v[26:29], v[168:171], v[216:219], v[26:29]
	v_mfma_f32_16x16x32_bf16 v[26:29], v[172:175], v[220:223], v[26:29]
	v_mfma_f32_16x16x32_bf16 v[14:17], v[142:145], v[224:227], v[14:17]
	v_mfma_f32_16x16x32_bf16 v[14:17], v[146:149], v[228:231], v[14:17]
	v_mfma_f32_16x16x32_bf16 v[10:13], v[168:171], v[224:227], v[10:13]
	v_mfma_f32_16x16x32_bf16 v[10:13], v[172:175], v[228:231], v[10:13]
	v_mfma_f32_16x16x32_bf16 v[54:57], v[176:179], v[192:195], v[54:57]
	v_mfma_f32_16x16x32_bf16 v[54:57], v[180:183], v[196:199], v[54:57]
	v_mfma_f32_16x16x32_bf16 v[50:53], v[184:187], v[192:195], v[50:53]
	v_mfma_f32_16x16x32_bf16 v[50:53], v[188:191], v[196:199], v[50:53]
	v_mfma_f32_16x16x32_bf16 v[38:41], v[176:179], v[200:203], v[38:41]
	v_mfma_f32_16x16x32_bf16 v[38:41], v[180:183], v[204:207], v[38:41]
	v_mfma_f32_16x16x32_bf16 v[34:37], v[184:187], v[200:203], v[34:37]
	v_mfma_f32_16x16x32_bf16 v[34:37], v[188:191], v[204:207], v[34:37]
	v_mfma_f32_16x16x32_bf16 v[22:25], v[176:179], v[216:219], v[22:25]
	v_mfma_f32_16x16x32_bf16 v[22:25], v[180:183], v[220:223], v[22:25]
	v_mfma_f32_16x16x32_bf16 v[18:21], v[184:187], v[216:219], v[18:21]
	v_mfma_f32_16x16x32_bf16 v[18:21], v[188:191], v[220:223], v[18:21]
	v_mfma_f32_16x16x32_bf16 v[6:9], v[176:179], v[224:227], v[6:9]
	v_mfma_f32_16x16x32_bf16 v[6:9], v[180:183], v[228:231], v[6:9]
	v_mfma_f32_16x16x32_bf16 v[2:5], v[184:187], v[224:227], v[2:5]
	v_mfma_f32_16x16x32_bf16 v[2:5], v[188:191], v[228:231], v[2:5]
	s_barrier
	s_add_i32 s29, s29, 2
	s_add_u32 s50, s50, 0x100
	s_addc_u32 s51, s51, 0
	s_add_u32 s17, s17, 0x100
	s_addc_u32 s23, s23, 0
	s_cmp_gt_u32 s29, 29

.LBB0_1606:
	s_ashr_i32 s51, s50, 31
	s_lshl_b64 s[8:9], s[50:51], 20
	v_readlane_b32 s10, v242, 2
	v_readlane_b32 s11, v242, 3
	s_add_u32 s1, s10, s8
	s_addc_u32 s10, s11, s9
	s_and_b64 s[8:9], s[14:15], exec
	s_cselect_b32 s23, s10, s65
	s_cselect_b32 s22, s1, s64
	s_ashr_i32 s49, s48, 31
	s_lshl_b64 s[8:9], s[48:49], 20
	s_add_u32 s8, s3, s8
	s_addc_u32 s9, s16, s9
	s_and_b64 s[10:11], s[14:15], exec
	s_cselect_b32 s1, s9, s67
	s_cselect_b32 s10, s8, s66
	s_add_u32 s64, s64, 0x80080
	s_addc_u32 s65, s65, 0
	s_add_u32 s11, s66, 0x100
	s_addc_u32 s24, s67, 0
	s_mov_b32 s25, -2
	s_cmp_lg_u64 s[42:43], 0
	s_cbranch_scc0 .Lsp_LBB01607_plp1607
	s_setprio 1
.Lsp_LBB01607_plp1607:
	s_add_u32 s14, s64, 0xfff80080
	s_addc_u32 s15, s65, -1
	s_add_i32 s26, 0, 0x10000
	s_cmp_eq_u32 s25, 28
	s_cselect_b32 s67, s23, s15
	s_cselect_b32 s66, s22, s14
	v_add_u32_e32 v147, s26, v144
	s_cselect_b32 s15, s1, s24
	s_cselect_b32 s14, s10, s11
	s_add_i32 s28, 0, 0x14000
	ds_read_b128 v[140:143], v147
	ds_read_b128 v[148:151], v147 offset:1024
	ds_read_b128 v[152:155], v147 offset:2048
	ds_read_b128 v[168:171], v147 offset:3072
	v_add_u32_e32 v147, s28, v144
	ds_read_b128 v[172:175], v147
	ds_read_b128 v[176:179], v147 offset:1024
	ds_read_b128 v[180:183], v147 offset:2048
	ds_read_b128 v[184:187], v147 offset:3072
	v_lshl_add_u64 v[156:157], s[64:65], 0, v[136:137]
	s_add_i32 m0, s13, 0xc000
	ds_read_b128 v[188:191], v146
	ds_read_b128 v[192:195], v146 offset:1024
	ds_read_b128 v[196:199], v146 offset:2048
	ds_read_b128 v[200:203], v146 offset:3072
	ds_read_b128 v[204:207], v146 offset:4096
	ds_read_b128 v[216:219], v146 offset:5120
	ds_read_b128 v[220:223], v146 offset:6144
	ds_read_b128 v[224:227], v146 offset:7168
	global_load_lds_dwordx4 v[156:157], off
	v_lshl_add_u64 v[156:157], s[64:65], 0, v[138:139]
	s_add_i32 m0, s13, 0xe000
	s_nop 0
	global_load_lds_dwordx4 v[156:157], off
	s_waitcnt vmcnt(8)
	s_waitcnt lgkmcnt(0)
	s_barrier
	s_waitcnt lgkmcnt(0)
	v_mfma_f32_16x16x32_bf16 v[126:129], v[140:143], v[188:191], 0
	v_mfma_f32_16x16x32_bf16 v[126:129], v[148:151], v[192:195], v[126:129]
	v_mfma_f32_16x16x32_bf16 v[122:125], v[152:155], v[188:191], 0
	v_mfma_f32_16x16x32_bf16 v[122:125], v[168:171], v[192:195], v[122:125]
	v_mfma_f32_16x16x32_bf16 v[110:113], v[140:143], v[196:199], 0
	v_mfma_f32_16x16x32_bf16 v[110:113], v[148:151], v[200:203], v[110:113]
	v_mfma_f32_16x16x32_bf16 v[106:109], v[152:155], v[196:199], 0
	v_mfma_f32_16x16x32_bf16 v[106:109], v[168:171], v[200:203], v[106:109]
	v_mfma_f32_16x16x32_bf16 v[94:97], v[140:143], v[204:207], 0
	v_mfma_f32_16x16x32_bf16 v[94:97], v[148:151], v[216:219], v[94:97]
	v_mfma_f32_16x16x32_bf16 v[90:93], v[152:155], v[204:207], 0
	v_mfma_f32_16x16x32_bf16 v[90:93], v[168:171], v[216:219], v[90:93]
	v_mfma_f32_16x16x32_bf16 v[78:81], v[140:143], v[220:223], 0
	v_mfma_f32_16x16x32_bf16 v[78:81], v[148:151], v[224:227], v[78:81]
	v_mfma_f32_16x16x32_bf16 v[74:77], v[152:155], v[220:223], 0
	v_mfma_f32_16x16x32_bf16 v[74:77], v[168:171], v[224:227], v[74:77]
	v_mfma_f32_16x16x32_bf16 v[118:121], v[172:175], v[188:191], 0
	v_mfma_f32_16x16x32_bf16 v[118:121], v[176:179], v[192:195], v[118:121]
	v_mfma_f32_16x16x32_bf16 v[114:117], v[180:183], v[188:191], 0
	v_mfma_f32_16x16x32_bf16 v[114:117], v[184:187], v[192:195], v[114:117]
	v_mfma_f32_16x16x32_bf16 v[102:105], v[172:175], v[196:199], 0
	v_mfma_f32_16x16x32_bf16 v[102:105], v[176:179], v[200:203], v[102:105]
	v_mfma_f32_16x16x32_bf16 v[98:101], v[180:183], v[196:199], 0
	v_mfma_f32_16x16x32_bf16 v[98:101], v[184:187], v[200:203], v[98:101]
	v_mfma_f32_16x16x32_bf16 v[86:89], v[172:175], v[204:207], 0
	v_mfma_f32_16x16x32_bf16 v[86:89], v[176:179], v[216:219], v[86:89]
	v_mfma_f32_16x16x32_bf16 v[82:85], v[180:183], v[204:207], 0
	v_mfma_f32_16x16x32_bf16 v[82:85], v[184:187], v[216:219], v[82:85]
	v_mfma_f32_16x16x32_bf16 v[70:73], v[172:175], v[220:223], 0
	v_mfma_f32_16x16x32_bf16 v[70:73], v[176:179], v[224:227], v[70:73]
	v_mfma_f32_16x16x32_bf16 v[66:69], v[180:183], v[220:223], 0
	v_mfma_f32_16x16x32_bf16 v[66:69], v[184:187], v[224:227], v[66:69]
	s_barrier
	s_add_i32 s26, s26, s17
	v_lshl_add_u64 v[156:157], s[14:15], 0, v[158:159]
	s_mov_b32 m0, s26
	ds_read_b128 v[188:191], v146 offset:16384
	ds_read_b128 v[192:195], v146 offset:17408
	ds_read_b128 v[196:199], v146 offset:18432
	ds_read_b128 v[200:203], v146 offset:19456
	ds_read_b128 v[204:207], v146 offset:20480
	ds_read_b128 v[216:219], v146 offset:21504
	ds_read_b128 v[220:223], v146 offset:22528
	ds_read_b128 v[224:227], v146 offset:23552
	global_load_lds_dwordx4 v[156:157], off
	s_add_i32 m0, s26, 0x2000
	s_add_u32 s26, s14, 0x80000
	v_lshl_add_u64 v[228:229], s[14:15], 0, v[134:135]
	s_addc_u32 s27, s15, 0
	s_add_i32 s28, s28, s17
	global_load_lds_dwordx4 v[228:229], off
	v_lshl_add_u64 v[230:231], s[26:27], 0, v[158:159]
	s_mov_b32 m0, s28
	v_lshl_add_u64 v[232:233], s[66:67], 0, v[132:133]
	global_load_lds_dwordx4 v[230:231], off
	v_lshl_add_u64 v[230:231], s[26:27], 0, v[134:135]
	s_add_i32 m0, s28, 0x2000
	s_nop 0
	global_load_lds_dwordx4 v[230:231], off
	v_lshl_add_u64 v[230:231], s[66:67], 0, v[130:131]
	s_mov_b32 m0, s13
	s_nop 0
	global_load_lds_dwordx4 v[230:231], off
	s_mov_b32 m0, s53
	s_nop 0
	global_load_lds_dwordx4 v[232:233], off
	s_waitcnt vmcnt(8)
	s_waitcnt lgkmcnt(0)
	s_barrier
	s_waitcnt lgkmcnt(0)
	v_mfma_f32_16x16x32_bf16 v[62:65], v[140:143], v[188:191], 0
	v_mfma_f32_16x16x32_bf16 v[62:65], v[148:151], v[192:195], v[62:65]
	v_mfma_f32_16x16x32_bf16 v[58:61], v[152:155], v[188:191], 0
	v_mfma_f32_16x16x32_bf16 v[58:61], v[168:171], v[192:195], v[58:61]
	v_mfma_f32_16x16x32_bf16 v[46:49], v[140:143], v[196:199], 0
	v_mfma_f32_16x16x32_bf16 v[46:49], v[148:151], v[200:203], v[46:49]
	v_mfma_f32_16x16x32_bf16 v[42:45], v[152:155], v[196:199], 0
	v_mfma_f32_16x16x32_bf16 v[42:45], v[168:171], v[200:203], v[42:45]
	v_mfma_f32_16x16x32_bf16 v[30:33], v[140:143], v[204:207], 0
	v_mfma_f32_16x16x32_bf16 v[30:33], v[148:151], v[216:219], v[30:33]
	v_mfma_f32_16x16x32_bf16 v[26:29], v[152:155], v[204:207], 0
	v_mfma_f32_16x16x32_bf16 v[26:29], v[168:171], v[216:219], v[26:29]
	v_mfma_f32_16x16x32_bf16 v[14:17], v[140:143], v[220:223], 0
	v_mfma_f32_16x16x32_bf16 v[14:17], v[148:151], v[224:227], v[14:17]
	v_mfma_f32_16x16x32_bf16 v[10:13], v[152:155], v[220:223], 0
	v_mfma_f32_16x16x32_bf16 v[10:13], v[168:171], v[224:227], v[10:13]
	v_mfma_f32_16x16x32_bf16 v[54:57], v[172:175], v[188:191], 0
	v_mfma_f32_16x16x32_bf16 v[54:57], v[176:179], v[192:195], v[54:57]
	v_mfma_f32_16x16x32_bf16 v[50:53], v[180:183], v[188:191], 0
	v_mfma_f32_16x16x32_bf16 v[50:53], v[184:187], v[192:195], v[50:53]
	v_mfma_f32_16x16x32_bf16 v[38:41], v[172:175], v[196:199], 0
	v_mfma_f32_16x16x32_bf16 v[38:41], v[176:179], v[200:203], v[38:41]
	v_mfma_f32_16x16x32_bf16 v[34:37], v[180:183], v[196:199], 0
	v_mfma_f32_16x16x32_bf16 v[34:37], v[184:187], v[200:203], v[34:37]
	v_mfma_f32_16x16x32_bf16 v[22:25], v[172:175], v[204:207], 0
	v_mfma_f32_16x16x32_bf16 v[22:25], v[176:179], v[216:219], v[22:25]
	v_mfma_f32_16x16x32_bf16 v[18:21], v[180:183], v[204:207], 0
	v_mfma_f32_16x16x32_bf16 v[18:21], v[184:187], v[216:219], v[18:21]
	v_mfma_f32_16x16x32_bf16 v[6:9], v[172:175], v[220:223], 0
	v_mfma_f32_16x16x32_bf16 v[6:9], v[176:179], v[224:227], v[6:9]
	v_mfma_f32_16x16x32_bf16 v[2:5], v[180:183], v[220:223], 0
	v_mfma_f32_16x16x32_bf16 v[2:5], v[184:187], v[224:227], v[2:5]
	s_barrier
	s_add_i32 s28, 0, 0x18000
	v_add_u32_e32 v147, s28, v144
	s_add_i32 s29, 0, 0x1c000
	ds_read_b128 v[140:143], v147
	ds_read_b128 v[148:151], v147 offset:1024
	ds_read_b128 v[152:155], v147 offset:2048
	ds_read_b128 v[168:171], v147 offset:3072
	v_add_u32_e32 v147, s29, v144
	ds_read_b128 v[172:175], v147
	ds_read_b128 v[176:179], v147 offset:1024
	ds_read_b128 v[180:183], v147 offset:2048
	ds_read_b128 v[184:187], v147 offset:3072
	s_add_u32 s26, s66, 0x80000
	s_addc_u32 s27, s67, 0
	s_mov_b32 m0, s58
	v_lshl_add_u64 v[234:235], s[26:27], 0, v[130:131]
	ds_read_b128 v[188:191], v146 offset:32768
	ds_read_b128 v[192:195], v146 offset:33792
	ds_read_b128 v[196:199], v146 offset:34816
	ds_read_b128 v[200:203], v146 offset:35840
	ds_read_b128 v[204:207], v146 offset:36864
	ds_read_b128 v[216:219], v146 offset:37888
	ds_read_b128 v[220:223], v146 offset:38912
	ds_read_b128 v[224:227], v146 offset:39936
	global_load_lds_dwordx4 v[234:235], off
	v_lshl_add_u64 v[234:235], s[26:27], 0, v[132:133]
	s_mov_b32 m0, s59
	s_nop 0
	global_load_lds_dwordx4 v[234:235], off
	s_waitcnt vmcnt(8)
	s_waitcnt lgkmcnt(0)
	s_barrier
	s_waitcnt lgkmcnt(0)
	v_mfma_f32_16x16x32_bf16 v[126:129], v[140:143], v[188:191], v[126:129]
	v_mfma_f32_16x16x32_bf16 v[126:129], v[148:151], v[192:195], v[126:129]
	v_mfma_f32_16x16x32_bf16 v[122:125], v[152:155], v[188:191], v[122:125]
	v_mfma_f32_16x16x32_bf16 v[122:125], v[168:171], v[192:195], v[122:125]
	v_mfma_f32_16x16x32_bf16 v[110:113], v[140:143], v[196:199], v[110:113]
	v_mfma_f32_16x16x32_bf16 v[110:113], v[148:151], v[200:203], v[110:113]
	v_mfma_f32_16x16x32_bf16 v[106:109], v[152:155], v[196:199], v[106:109]
	v_mfma_f32_16x16x32_bf16 v[106:109], v[168:171], v[200:203], v[106:109]
	v_mfma_f32_16x16x32_bf16 v[94:97], v[140:143], v[204:207], v[94:97]
	v_mfma_f32_16x16x32_bf16 v[94:97], v[148:151], v[216:219], v[94:97]
	v_mfma_f32_16x16x32_bf16 v[90:93], v[152:155], v[204:207], v[90:93]
	v_mfma_f32_16x16x32_bf16 v[90:93], v[168:171], v[216:219], v[90:93]
	v_mfma_f32_16x16x32_bf16 v[78:81], v[140:143], v[220:223], v[78:81]
	v_mfma_f32_16x16x32_bf16 v[78:81], v[148:151], v[224:227], v[78:81]
	v_mfma_f32_16x16x32_bf16 v[74:77], v[152:155], v[220:223], v[74:77]
	v_mfma_f32_16x16x32_bf16 v[74:77], v[168:171], v[224:227], v[74:77]
	v_mfma_f32_16x16x32_bf16 v[118:121], v[172:175], v[188:191], v[118:121]
	v_mfma_f32_16x16x32_bf16 v[118:121], v[176:179], v[192:195], v[118:121]
	v_mfma_f32_16x16x32_bf16 v[114:117], v[180:183], v[188:191], v[114:117]
	v_mfma_f32_16x16x32_bf16 v[114:117], v[184:187], v[192:195], v[114:117]
	v_mfma_f32_16x16x32_bf16 v[102:105], v[172:175], v[196:199], v[102:105]
	v_mfma_f32_16x16x32_bf16 v[102:105], v[176:179], v[200:203], v[102:105]
	v_mfma_f32_16x16x32_bf16 v[98:101], v[180:183], v[196:199], v[98:101]
	v_mfma_f32_16x16x32_bf16 v[98:101], v[184:187], v[200:203], v[98:101]
	v_mfma_f32_16x16x32_bf16 v[86:89], v[172:175], v[204:207], v[86:89]
	v_mfma_f32_16x16x32_bf16 v[86:89], v[176:179], v[216:219], v[86:89]
	v_mfma_f32_16x16x32_bf16 v[82:85], v[180:183], v[204:207], v[82:85]
	v_mfma_f32_16x16x32_bf16 v[82:85], v[184:187], v[216:219], v[82:85]
	v_mfma_f32_16x16x32_bf16 v[70:73], v[172:175], v[220:223], v[70:73]
	v_mfma_f32_16x16x32_bf16 v[70:73], v[176:179], v[224:227], v[70:73]
	v_mfma_f32_16x16x32_bf16 v[66:69], v[180:183], v[220:223], v[66:69]
	v_mfma_f32_16x16x32_bf16 v[66:69], v[184:187], v[224:227], v[66:69]
	s_barrier
	s_add_i32 s26, s28, s17
	v_lshl_add_u64 v[156:157], v[156:157], 0, s[56:57]
	s_mov_b32 m0, s26
	ds_read_b128 v[188:191], v146 offset:49152
	ds_read_b128 v[192:195], v146 offset:50176
	ds_read_b128 v[196:199], v146 offset:51200
	ds_read_b128 v[200:203], v146 offset:52224
	ds_read_b128 v[204:207], v146 offset:53248
	ds_read_b128 v[216:219], v146 offset:54272
	ds_read_b128 v[220:223], v146 offset:55296
	ds_read_b128 v[224:227], v146 offset:56320
	global_load_lds_dwordx4 v[156:157], off
	s_add_i32 m0, s26, 0x2000
	s_add_u32 s14, s14, 0x80080
	v_lshl_add_u64 v[156:157], v[228:229], 0, s[56:57]
	s_addc_u32 s15, s15, 0
	s_add_i32 s26, s29, s17
	global_load_lds_dwordx4 v[156:157], off
	v_lshl_add_u64 v[156:157], s[14:15], 0, v[158:159]
	s_mov_b32 m0, s26
	s_nop 0
	global_load_lds_dwordx4 v[156:157], off
	v_lshl_add_u64 v[156:157], s[14:15], 0, v[134:135]
	s_add_i32 m0, s26, 0x2000
	s_nop 0
	global_load_lds_dwordx4 v[156:157], off
	v_lshl_add_u64 v[156:157], v[230:231], 0, s[56:57]
	s_mov_b32 m0, s54
	s_nop 0
	global_load_lds_dwordx4 v[156:157], off
	v_lshl_add_u64 v[156:157], v[232:233], 0, s[56:57]
	s_mov_b32 m0, s68
	s_nop 0
	global_load_lds_dwordx4 v[156:157], off
	s_waitcnt vmcnt(8)
	s_waitcnt lgkmcnt(0)
	s_barrier
	s_waitcnt lgkmcnt(0)
	v_mfma_f32_16x16x32_bf16 v[62:65], v[140:143], v[188:191], v[62:65]
	v_mfma_f32_16x16x32_bf16 v[62:65], v[148:151], v[192:195], v[62:65]
	v_mfma_f32_16x16x32_bf16 v[58:61], v[152:155], v[188:191], v[58:61]
	v_mfma_f32_16x16x32_bf16 v[58:61], v[168:171], v[192:195], v[58:61]
	v_mfma_f32_16x16x32_bf16 v[46:49], v[140:143], v[196:199], v[46:49]
	v_mfma_f32_16x16x32_bf16 v[46:49], v[148:151], v[200:203], v[46:49]
	v_mfma_f32_16x16x32_bf16 v[42:45], v[152:155], v[196:199], v[42:45]
	v_mfma_f32_16x16x32_bf16 v[42:45], v[168:171], v[200:203], v[42:45]
	v_mfma_f32_16x16x32_bf16 v[30:33], v[140:143], v[204:207], v[30:33]
	v_mfma_f32_16x16x32_bf16 v[30:33], v[148:151], v[216:219], v[30:33]
	v_mfma_f32_16x16x32_bf16 v[26:29], v[152:155], v[204:207], v[26:29]
	v_mfma_f32_16x16x32_bf16 v[26:29], v[168:171], v[216:219], v[26:29]
	v_mfma_f32_16x16x32_bf16 v[14:17], v[140:143], v[220:223], v[14:17]
	v_mfma_f32_16x16x32_bf16 v[14:17], v[148:151], v[224:227], v[14:17]
	v_mfma_f32_16x16x32_bf16 v[10:13], v[152:155], v[220:223], v[10:13]
	v_mfma_f32_16x16x32_bf16 v[10:13], v[168:171], v[224:227], v[10:13]
	v_mfma_f32_16x16x32_bf16 v[54:57], v[172:175], v[188:191], v[54:57]
	v_mfma_f32_16x16x32_bf16 v[54:57], v[176:179], v[192:195], v[54:57]
	v_mfma_f32_16x16x32_bf16 v[50:53], v[180:183], v[188:191], v[50:53]
	v_mfma_f32_16x16x32_bf16 v[50:53], v[184:187], v[192:195], v[50:53]
	v_mfma_f32_16x16x32_bf16 v[38:41], v[172:175], v[196:199], v[38:41]
	v_mfma_f32_16x16x32_bf16 v[38:41], v[176:179], v[200:203], v[38:41]
	v_mfma_f32_16x16x32_bf16 v[34:37], v[180:183], v[196:199], v[34:37]
	v_mfma_f32_16x16x32_bf16 v[34:37], v[184:187], v[200:203], v[34:37]
	v_mfma_f32_16x16x32_bf16 v[22:25], v[172:175], v[204:207], v[22:25]
	v_mfma_f32_16x16x32_bf16 v[22:25], v[176:179], v[216:219], v[22:25]
	v_mfma_f32_16x16x32_bf16 v[18:21], v[180:183], v[204:207], v[18:21]
	v_mfma_f32_16x16x32_bf16 v[18:21], v[184:187], v[216:219], v[18:21]
	v_mfma_f32_16x16x32_bf16 v[6:9], v[172:175], v[220:223], v[6:9]
	v_mfma_f32_16x16x32_bf16 v[6:9], v[176:179], v[224:227], v[6:9]
	v_mfma_f32_16x16x32_bf16 v[2:5], v[180:183], v[220:223], v[2:5]
	v_mfma_f32_16x16x32_bf16 v[2:5], v[184:187], v[224:227], v[2:5]
	s_barrier
	s_add_i32 s25, s25, 2
	s_add_u32 s64, s64, 0x100
	s_addc_u32 s65, s65, 0
	s_add_u32 s11, s11, 0x100
	s_addc_u32 s24, s24, 0
	s_cmp_gt_u32 s25, 29
